# kpair + 28 of 64 GEMM LDS-DMA loads in SGPR-base + 32-bit VGPR offset form (drops the 64-bit VALU address adds)
# speedup vs baseline: 1.0081x; 1.0038x over previous
.LBB0_120:
	s_add_u32 s28, s40, 0xfff80080
	s_addc_u32 s29, s41, -1
	s_add_i32 s54, 0, 0x10000
	s_cmp_eq_u32 s53, 28
	s_cselect_b32 s29, s23, s29
	s_cselect_b32 s28, s22, s28
	s_cselect_b32 s43, s21, s52
	s_cselect_b32 s42, s50, s51
	s_add_i32 s56, 0, 0x14000
	v_add_u32_e32 v142, s54, v212
	v_add_u32_e32 v158, s56, v212
	ds_read_b128 v[130:133], v142
	ds_read_b128 v[134:137], v142 offset:1024
	ds_read_b128 v[138:141], v142 offset:2048
	ds_read_b128 v[142:145], v142 offset:3072
	ds_read_b128 v[146:149], v158
	ds_read_b128 v[150:153], v158 offset:1024
	ds_read_b128 v[154:157], v158 offset:2048
	ds_read_b128 v[158:161], v158 offset:3072
	s_add_i32 m0, s24, 0xc000
	ds_read_b128 v[162:165], v213
	ds_read_b128 v[166:169], v213 offset:1024
	ds_read_b128 v[170:173], v213 offset:2048
	ds_read_b128 v[174:177], v213 offset:3072
	ds_read_b128 v[188:191], v213 offset:4096
	ds_read_b128 v[192:195], v213 offset:5120
	ds_read_b128 v[196:199], v213 offset:6144
	ds_read_b128 v[200:203], v213 offset:7168
	global_load_lds_dwordx4 v184, s[40:41]
	s_add_i32 m0, s24, 0xe000
	s_nop 0
	global_load_lds_dwordx4 v186, s[40:41]
	s_waitcnt vmcnt(8)
	s_waitcnt lgkmcnt(0)
	s_barrier
	s_setprio 1
	s_waitcnt lgkmcnt(0)
	v_mfma_f32_16x16x32_bf16 v[126:129], v[130:133], v[162:165], v[126:129]
	v_mfma_f32_16x16x32_bf16 v[126:129], v[134:137], v[166:169], v[126:129]
	v_mfma_f32_16x16x32_bf16 v[122:125], v[142:145], v[166:169], v[122:125]
	v_mfma_f32_16x16x32_bf16 v[122:125], v[138:141], v[162:165], v[122:125]
	v_mfma_f32_16x16x32_bf16 v[106:109], v[138:141], v[170:173], v[106:109]
	v_mfma_f32_16x16x32_bf16 v[106:109], v[142:145], v[174:177], v[106:109]
	v_mfma_f32_16x16x32_bf16 v[110:113], v[134:137], v[174:177], v[110:113]
	v_mfma_f32_16x16x32_bf16 v[110:113], v[130:133], v[170:173], v[110:113]
	v_mfma_f32_16x16x32_bf16 v[94:97], v[130:133], v[188:191], v[94:97]
	v_mfma_f32_16x16x32_bf16 v[94:97], v[134:137], v[192:195], v[94:97]
	v_mfma_f32_16x16x32_bf16 v[90:93], v[142:145], v[192:195], v[90:93]
	v_mfma_f32_16x16x32_bf16 v[90:93], v[138:141], v[188:191], v[90:93]
	v_mfma_f32_16x16x32_bf16 v[74:77], v[138:141], v[196:199], v[74:77]
	v_mfma_f32_16x16x32_bf16 v[74:77], v[142:145], v[200:203], v[74:77]
	v_mfma_f32_16x16x32_bf16 v[78:81], v[134:137], v[200:203], v[78:81]
	v_mfma_f32_16x16x32_bf16 v[78:81], v[130:133], v[196:199], v[78:81]
	s_setprio 0
	s_setprio 1
	v_mfma_f32_16x16x32_bf16 v[118:121], v[146:149], v[162:165], v[118:121]
	v_mfma_f32_16x16x32_bf16 v[118:121], v[150:153], v[166:169], v[118:121]
	v_mfma_f32_16x16x32_bf16 v[114:117], v[158:161], v[166:169], v[114:117]
	v_mfma_f32_16x16x32_bf16 v[114:117], v[154:157], v[162:165], v[114:117]
	v_mfma_f32_16x16x32_bf16 v[98:101], v[154:157], v[170:173], v[98:101]
	v_mfma_f32_16x16x32_bf16 v[98:101], v[158:161], v[174:177], v[98:101]
	v_mfma_f32_16x16x32_bf16 v[102:105], v[150:153], v[174:177], v[102:105]
	v_mfma_f32_16x16x32_bf16 v[102:105], v[146:149], v[170:173], v[102:105]
	v_mfma_f32_16x16x32_bf16 v[86:89], v[146:149], v[188:191], v[86:89]
	v_mfma_f32_16x16x32_bf16 v[86:89], v[150:153], v[192:195], v[86:89]
	v_mfma_f32_16x16x32_bf16 v[82:85], v[158:161], v[192:195], v[82:85]
	v_mfma_f32_16x16x32_bf16 v[82:85], v[154:157], v[188:191], v[82:85]
	v_mfma_f32_16x16x32_bf16 v[66:69], v[154:157], v[196:199], v[66:69]
	v_mfma_f32_16x16x32_bf16 v[66:69], v[158:161], v[200:203], v[66:69]
	v_mfma_f32_16x16x32_bf16 v[70:73], v[150:153], v[200:203], v[70:73]
	v_mfma_f32_16x16x32_bf16 v[70:73], v[146:149], v[196:199], v[70:73]
	s_setprio 0
	s_barrier
	s_add_i32 s54, s54, s1
	v_lshl_add_u64 v[204:205], s[42:43], 0, v[32:33]
	s_mov_b32 m0, s54
	ds_read_b128 v[162:165], v213 offset:16384
	ds_read_b128 v[166:169], v213 offset:17408
	ds_read_b128 v[170:173], v213 offset:18432
	ds_read_b128 v[174:177], v213 offset:19456
	ds_read_b128 v[188:191], v213 offset:20480
	ds_read_b128 v[192:195], v213 offset:21504
	ds_read_b128 v[196:199], v213 offset:22528
	ds_read_b128 v[200:203], v213 offset:23552
	global_load_lds_dwordx4 v[204:205], off
	s_add_i32 m0, s54, 0x2000
	s_add_u32 s54, s42, 0x80000
	v_lshl_add_u64 v[206:207], s[42:43], 0, v[182:183]
	s_addc_u32 s55, s43, 0
	s_add_i32 s56, s56, s1
	global_load_lds_dwordx4 v[206:207], off
	s_mov_b32 m0, s56
	v_lshl_add_u64 v[214:215], s[28:29], 0, v[180:181]
	global_load_lds_dwordx4 v32, s[54:55]
	s_add_i32 m0, s56, 0x2000
	s_nop 0
	global_load_lds_dwordx4 v182, s[54:55]
	v_lshl_add_u64 v[208:209], s[28:29], 0, v[178:179]
	s_mov_b32 m0, s24
	s_nop 0
	global_load_lds_dwordx4 v[208:209], off
	s_mov_b32 m0, s25
	s_nop 0
	global_load_lds_dwordx4 v[214:215], off
	s_waitcnt vmcnt(8)
	s_waitcnt lgkmcnt(0)
	s_barrier
	s_setprio 1
	s_waitcnt lgkmcnt(0)
	v_mfma_f32_16x16x32_bf16 v[62:65], v[130:133], v[162:165], v[62:65]
	v_mfma_f32_16x16x32_bf16 v[62:65], v[134:137], v[166:169], v[62:65]
	v_mfma_f32_16x16x32_bf16 v[58:61], v[142:145], v[166:169], v[58:61]
	v_mfma_f32_16x16x32_bf16 v[58:61], v[138:141], v[162:165], v[58:61]
	v_mfma_f32_16x16x32_bf16 v[42:45], v[138:141], v[170:173], v[42:45]
	v_mfma_f32_16x16x32_bf16 v[42:45], v[142:145], v[174:177], v[42:45]
	v_mfma_f32_16x16x32_bf16 v[46:49], v[134:137], v[174:177], v[46:49]
	v_mfma_f32_16x16x32_bf16 v[46:49], v[130:133], v[170:173], v[46:49]
	v_mfma_f32_16x16x32_bf16 v[28:31], v[130:133], v[188:191], v[28:31]
	v_mfma_f32_16x16x32_bf16 v[28:31], v[134:137], v[192:195], v[28:31]
	v_mfma_f32_16x16x32_bf16 v[24:27], v[142:145], v[192:195], v[24:27]
	v_mfma_f32_16x16x32_bf16 v[24:27], v[138:141], v[188:191], v[24:27]
	v_mfma_f32_16x16x32_bf16 v[8:11], v[138:141], v[196:199], v[8:11]
	v_mfma_f32_16x16x32_bf16 v[8:11], v[142:145], v[200:203], v[8:11]
	v_mfma_f32_16x16x32_bf16 v[12:15], v[134:137], v[200:203], v[12:15]
	v_mfma_f32_16x16x32_bf16 v[12:15], v[130:133], v[196:199], v[12:15]
	s_setprio 0
	s_setprio 1
	v_mfma_f32_16x16x32_bf16 v[54:57], v[146:149], v[162:165], v[54:57]
	v_mfma_f32_16x16x32_bf16 v[54:57], v[150:153], v[166:169], v[54:57]
	v_mfma_f32_16x16x32_bf16 v[50:53], v[158:161], v[166:169], v[50:53]
	v_mfma_f32_16x16x32_bf16 v[50:53], v[154:157], v[162:165], v[50:53]
	v_mfma_f32_16x16x32_bf16 v[34:37], v[154:157], v[170:173], v[34:37]
	v_mfma_f32_16x16x32_bf16 v[34:37], v[158:161], v[174:177], v[34:37]
	v_mfma_f32_16x16x32_bf16 v[38:41], v[150:153], v[174:177], v[38:41]
	v_mfma_f32_16x16x32_bf16 v[38:41], v[146:149], v[170:173], v[38:41]
	v_mfma_f32_16x16x32_bf16 v[20:23], v[146:149], v[188:191], v[20:23]
	v_mfma_f32_16x16x32_bf16 v[20:23], v[150:153], v[192:195], v[20:23]
	v_mfma_f32_16x16x32_bf16 v[16:19], v[158:161], v[192:195], v[16:19]
	v_mfma_f32_16x16x32_bf16 v[16:19], v[154:157], v[188:191], v[16:19]
	v_mfma_f32_16x16x32_bf16 v[0:3], v[154:157], v[196:199], v[0:3]
	v_mfma_f32_16x16x32_bf16 v[0:3], v[158:161], v[200:203], v[0:3]
	v_mfma_f32_16x16x32_bf16 v[4:7], v[150:153], v[200:203], v[4:7]
	v_mfma_f32_16x16x32_bf16 v[4:7], v[146:149], v[196:199], v[4:7]
	s_setprio 0
	s_barrier
	s_add_i32 s54, 0, 0x18000
	s_add_i32 s55, 0, 0x1c000
	v_add_u32_e32 v142, s54, v212
	v_add_u32_e32 v158, s55, v212
	ds_read_b128 v[130:133], v142
	ds_read_b128 v[134:137], v142 offset:1024
	ds_read_b128 v[138:141], v142 offset:2048
	ds_read_b128 v[142:145], v142 offset:3072
	ds_read_b128 v[146:149], v158
	ds_read_b128 v[150:153], v158 offset:1024
	ds_read_b128 v[154:157], v158 offset:2048
	ds_read_b128 v[158:161], v158 offset:3072
	s_add_u32 s28, s28, 0x80000
	s_addc_u32 s29, s29, 0
	s_mov_b32 m0, s33
	ds_read_b128 v[162:165], v213 offset:32768
	ds_read_b128 v[166:169], v213 offset:33792
	ds_read_b128 v[170:173], v213 offset:34816
	ds_read_b128 v[174:177], v213 offset:35840
	ds_read_b128 v[188:191], v213 offset:36864
	ds_read_b128 v[192:195], v213 offset:37888
	ds_read_b128 v[196:199], v213 offset:38912
	ds_read_b128 v[200:203], v213 offset:39936
	global_load_lds_dwordx4 v178, s[28:29]
	s_mov_b32 m0, s36
	s_nop 0
	global_load_lds_dwordx4 v180, s[28:29]
	s_waitcnt vmcnt(8)
	s_waitcnt lgkmcnt(0)
	s_barrier
	s_setprio 1
	s_waitcnt lgkmcnt(0)
	v_mfma_f32_16x16x32_bf16 v[126:129], v[130:133], v[162:165], v[126:129]
	v_mfma_f32_16x16x32_bf16 v[126:129], v[134:137], v[166:169], v[126:129]
	v_mfma_f32_16x16x32_bf16 v[122:125], v[142:145], v[166:169], v[122:125]
	v_mfma_f32_16x16x32_bf16 v[122:125], v[138:141], v[162:165], v[122:125]
	v_mfma_f32_16x16x32_bf16 v[106:109], v[138:141], v[170:173], v[106:109]
	v_mfma_f32_16x16x32_bf16 v[106:109], v[142:145], v[174:177], v[106:109]
	v_mfma_f32_16x16x32_bf16 v[110:113], v[134:137], v[174:177], v[110:113]
	v_mfma_f32_16x16x32_bf16 v[110:113], v[130:133], v[170:173], v[110:113]
	v_mfma_f32_16x16x32_bf16 v[94:97], v[130:133], v[188:191], v[94:97]
	v_mfma_f32_16x16x32_bf16 v[94:97], v[134:137], v[192:195], v[94:97]
	v_mfma_f32_16x16x32_bf16 v[90:93], v[142:145], v[192:195], v[90:93]
	v_mfma_f32_16x16x32_bf16 v[90:93], v[138:141], v[188:191], v[90:93]
	v_mfma_f32_16x16x32_bf16 v[74:77], v[138:141], v[196:199], v[74:77]
	v_mfma_f32_16x16x32_bf16 v[74:77], v[142:145], v[200:203], v[74:77]
	v_mfma_f32_16x16x32_bf16 v[78:81], v[134:137], v[200:203], v[78:81]
	v_mfma_f32_16x16x32_bf16 v[78:81], v[130:133], v[196:199], v[78:81]
	s_setprio 0
	s_setprio 1
	v_mfma_f32_16x16x32_bf16 v[118:121], v[146:149], v[162:165], v[118:121]
	v_mfma_f32_16x16x32_bf16 v[118:121], v[150:153], v[166:169], v[118:121]
	v_mfma_f32_16x16x32_bf16 v[114:117], v[158:161], v[166:169], v[114:117]
	v_mfma_f32_16x16x32_bf16 v[114:117], v[154:157], v[162:165], v[114:117]
	v_mfma_f32_16x16x32_bf16 v[98:101], v[154:157], v[170:173], v[98:101]
	v_mfma_f32_16x16x32_bf16 v[98:101], v[158:161], v[174:177], v[98:101]
	v_mfma_f32_16x16x32_bf16 v[102:105], v[150:153], v[174:177], v[102:105]
	v_mfma_f32_16x16x32_bf16 v[102:105], v[146:149], v[170:173], v[102:105]
	v_mfma_f32_16x16x32_bf16 v[86:89], v[146:149], v[188:191], v[86:89]
	v_mfma_f32_16x16x32_bf16 v[86:89], v[150:153], v[192:195], v[86:89]
	v_mfma_f32_16x16x32_bf16 v[82:85], v[158:161], v[192:195], v[82:85]
	v_mfma_f32_16x16x32_bf16 v[82:85], v[154:157], v[188:191], v[82:85]
	v_mfma_f32_16x16x32_bf16 v[66:69], v[154:157], v[196:199], v[66:69]
	v_mfma_f32_16x16x32_bf16 v[66:69], v[158:161], v[200:203], v[66:69]
	v_mfma_f32_16x16x32_bf16 v[70:73], v[150:153], v[200:203], v[70:73]
	v_mfma_f32_16x16x32_bf16 v[70:73], v[146:149], v[196:199], v[70:73]
	s_setprio 0
	s_barrier
	s_add_i32 s28, s54, s1
	v_lshl_add_u64 v[204:205], v[204:205], 0, s[34:35]
	s_mov_b32 m0, s28
	ds_read_b128 v[162:165], v213 offset:49152
	ds_read_b128 v[166:169], v213 offset:50176
	ds_read_b128 v[170:173], v213 offset:51200
	ds_read_b128 v[174:177], v213 offset:52224
	ds_read_b128 v[188:191], v213 offset:53248
	ds_read_b128 v[192:195], v213 offset:54272
	ds_read_b128 v[196:199], v213 offset:55296
	ds_read_b128 v[200:203], v213 offset:56320
	global_load_lds_dwordx4 v[204:205], off
	s_add_i32 m0, s28, 0x2000
	s_add_u32 s28, s42, 0x80080
	v_lshl_add_u64 v[204:205], v[206:207], 0, s[34:35]
	s_addc_u32 s29, s43, 0
	s_add_i32 s42, s55, s1
	global_load_lds_dwordx4 v[204:205], off
	s_mov_b32 m0, s42
	s_nop 0
	global_load_lds_dwordx4 v32, s[28:29]
	s_add_i32 m0, s42, 0x2000
	s_nop 0
	global_load_lds_dwordx4 v182, s[28:29]
	v_lshl_add_u64 v[204:205], v[208:209], 0, s[34:35]
	s_mov_b32 m0, s44
	s_nop 0
	global_load_lds_dwordx4 v[204:205], off
	v_lshl_add_u64 v[204:205], v[214:215], 0, s[34:35]
	s_mov_b32 m0, s45
	s_nop 0
	global_load_lds_dwordx4 v[204:205], off
	s_waitcnt vmcnt(8)
	s_waitcnt lgkmcnt(0)
	s_barrier
	s_setprio 1
	s_waitcnt lgkmcnt(0)
	v_mfma_f32_16x16x32_bf16 v[62:65], v[130:133], v[162:165], v[62:65]
	v_mfma_f32_16x16x32_bf16 v[62:65], v[134:137], v[166:169], v[62:65]
	v_mfma_f32_16x16x32_bf16 v[58:61], v[142:145], v[166:169], v[58:61]
	v_mfma_f32_16x16x32_bf16 v[58:61], v[138:141], v[162:165], v[58:61]
	v_mfma_f32_16x16x32_bf16 v[42:45], v[138:141], v[170:173], v[42:45]
	v_mfma_f32_16x16x32_bf16 v[42:45], v[142:145], v[174:177], v[42:45]
	v_mfma_f32_16x16x32_bf16 v[46:49], v[134:137], v[174:177], v[46:49]
	v_mfma_f32_16x16x32_bf16 v[46:49], v[130:133], v[170:173], v[46:49]
	v_mfma_f32_16x16x32_bf16 v[28:31], v[130:133], v[188:191], v[28:31]
	v_mfma_f32_16x16x32_bf16 v[28:31], v[134:137], v[192:195], v[28:31]
	v_mfma_f32_16x16x32_bf16 v[24:27], v[142:145], v[192:195], v[24:27]
	v_mfma_f32_16x16x32_bf16 v[24:27], v[138:141], v[188:191], v[24:27]
	v_mfma_f32_16x16x32_bf16 v[8:11], v[138:141], v[196:199], v[8:11]
	v_mfma_f32_16x16x32_bf16 v[8:11], v[142:145], v[200:203], v[8:11]
	v_mfma_f32_16x16x32_bf16 v[12:15], v[134:137], v[200:203], v[12:15]
	v_mfma_f32_16x16x32_bf16 v[12:15], v[130:133], v[196:199], v[12:15]
	s_setprio 0
	s_setprio 1
	v_mfma_f32_16x16x32_bf16 v[54:57], v[146:149], v[162:165], v[54:57]
	v_mfma_f32_16x16x32_bf16 v[54:57], v[150:153], v[166:169], v[54:57]
	v_mfma_f32_16x16x32_bf16 v[50:53], v[158:161], v[166:169], v[50:53]
	v_mfma_f32_16x16x32_bf16 v[50:53], v[154:157], v[162:165], v[50:53]
	v_mfma_f32_16x16x32_bf16 v[34:37], v[154:157], v[170:173], v[34:37]
	v_mfma_f32_16x16x32_bf16 v[34:37], v[158:161], v[174:177], v[34:37]
	v_mfma_f32_16x16x32_bf16 v[38:41], v[150:153], v[174:177], v[38:41]
	v_mfma_f32_16x16x32_bf16 v[38:41], v[146:149], v[170:173], v[38:41]
	v_mfma_f32_16x16x32_bf16 v[20:23], v[146:149], v[188:191], v[20:23]
	v_mfma_f32_16x16x32_bf16 v[20:23], v[150:153], v[192:195], v[20:23]
	v_mfma_f32_16x16x32_bf16 v[16:19], v[158:161], v[192:195], v[16:19]
	v_mfma_f32_16x16x32_bf16 v[16:19], v[154:157], v[188:191], v[16:19]
	v_mfma_f32_16x16x32_bf16 v[0:3], v[154:157], v[196:199], v[0:3]
	v_mfma_f32_16x16x32_bf16 v[0:3], v[158:161], v[200:203], v[0:3]
	v_mfma_f32_16x16x32_bf16 v[4:7], v[150:153], v[200:203], v[4:7]
	v_mfma_f32_16x16x32_bf16 v[4:7], v[146:149], v[196:199], v[4:7]
	s_setprio 0
	s_barrier
	s_add_i32 s53, s53, 2
	s_add_u32 s40, s40, 0x100
	s_addc_u32 s41, s41, 0
	s_add_u32 s51, s51, 0x100
	s_addc_u32 s52, s52, 0
	s_cmp_gt_u32 s53, 29
	s_cbranch_scc0 .LBB0_120
	s_and_b64 vcc, exec, s[18:19]
	s_cbranch_vccz .LBB0_123
	s_barrier

.LBB0_685:
	s_add_u32 s28, s16, s40
	s_addc_u32 s29, s17, s41
	s_add_u32 s28, s28, 0x100
	s_addc_u32 s29, s29, 0
	s_add_u32 s42, s52, s40
	s_addc_u32 s43, s53, s41
	s_add_i32 s56, 0, 0x10000
	s_cmpk_eq_i32 s40, 0xf00
	s_cselect_b32 s29, s39, s29
	s_cselect_b32 s28, s38, s28
	s_cselect_b32 s43, s23, s43
	s_cselect_b32 s42, s54, s42
	s_add_i32 s58, 0, 0x14000
	v_add_u32_e32 v146, s56, v190
	v_add_u32_e32 v162, s58, v190
	ds_read_b128 v[134:137], v146
	ds_read_b128 v[138:141], v146 offset:1024
	ds_read_b128 v[142:145], v146 offset:2048
	ds_read_b128 v[146:149], v146 offset:3072
	ds_read_b128 v[150:153], v162
	ds_read_b128 v[154:157], v162 offset:1024
	ds_read_b128 v[158:161], v162 offset:2048
	ds_read_b128 v[162:165], v162 offset:3072
	v_lshl_add_u64 v[212:213], v[130:131], 0, s[40:41]
	s_add_i32 m0, s24, 0xc000
	ds_read_b128 v[166:169], v191
	ds_read_b128 v[180:183], v191 offset:1024
	ds_read_b128 v[184:187], v191 offset:2048
	ds_read_b128 v[192:195], v191 offset:3072
	ds_read_b128 v[196:199], v191 offset:4096
	ds_read_b128 v[200:203], v191 offset:5120
	ds_read_b128 v[204:207], v191 offset:6144
	ds_read_b128 v[208:211], v191 offset:7168
	global_load_lds_dwordx4 v[212:213], off
	v_lshl_add_u64 v[212:213], v[132:133], 0, s[40:41]
	s_add_i32 m0, s24, 0xe000
	s_nop 0
	global_load_lds_dwordx4 v[212:213], off
	s_waitcnt vmcnt(8)
	s_waitcnt lgkmcnt(0)
	s_barrier
	s_setprio 1
	s_waitcnt lgkmcnt(0)
	v_mfma_f32_16x16x32_bf16 v[82:85], v[134:137], v[166:169], v[82:85]
	v_mfma_f32_16x16x32_bf16 v[82:85], v[138:141], v[180:183], v[82:85]
	v_mfma_f32_16x16x32_bf16 v[78:81], v[146:149], v[180:183], v[78:81]
	v_mfma_f32_16x16x32_bf16 v[78:81], v[142:145], v[166:169], v[78:81]
	v_mfma_f32_16x16x32_bf16 v[70:73], v[142:145], v[184:187], v[70:73]
	v_mfma_f32_16x16x32_bf16 v[70:73], v[146:149], v[192:195], v[70:73]
	v_mfma_f32_16x16x32_bf16 v[74:77], v[138:141], v[192:195], v[74:77]
	v_mfma_f32_16x16x32_bf16 v[74:77], v[134:137], v[184:187], v[74:77]
	v_mfma_f32_16x16x32_bf16 v[66:69], v[134:137], v[196:199], v[66:69]
	v_mfma_f32_16x16x32_bf16 v[66:69], v[138:141], v[200:203], v[66:69]
	v_mfma_f32_16x16x32_bf16 v[62:65], v[146:149], v[200:203], v[62:65]
	v_mfma_f32_16x16x32_bf16 v[62:65], v[142:145], v[196:199], v[62:65]
	v_mfma_f32_16x16x32_bf16 v[54:57], v[142:145], v[204:207], v[54:57]
	v_mfma_f32_16x16x32_bf16 v[54:57], v[146:149], v[208:211], v[54:57]
	v_mfma_f32_16x16x32_bf16 v[58:61], v[138:141], v[208:211], v[58:61]
	v_mfma_f32_16x16x32_bf16 v[58:61], v[134:137], v[204:207], v[58:61]
	s_setprio 0
	s_setprio 1
	v_mfma_f32_16x16x32_bf16 v[50:53], v[150:153], v[166:169], v[50:53]
	v_mfma_f32_16x16x32_bf16 v[50:53], v[154:157], v[180:183], v[50:53]
	v_mfma_f32_16x16x32_bf16 v[46:49], v[162:165], v[180:183], v[46:49]
	v_mfma_f32_16x16x32_bf16 v[46:49], v[158:161], v[166:169], v[46:49]
	v_mfma_f32_16x16x32_bf16 v[38:41], v[158:161], v[184:187], v[38:41]
	v_mfma_f32_16x16x32_bf16 v[38:41], v[162:165], v[192:195], v[38:41]
	v_mfma_f32_16x16x32_bf16 v[42:45], v[154:157], v[192:195], v[42:45]
	v_mfma_f32_16x16x32_bf16 v[42:45], v[150:153], v[184:187], v[42:45]
	v_mfma_f32_16x16x32_bf16 v[34:37], v[150:153], v[196:199], v[34:37]
	v_mfma_f32_16x16x32_bf16 v[34:37], v[154:157], v[200:203], v[34:37]
	v_mfma_f32_16x16x32_bf16 v[28:31], v[162:165], v[200:203], v[28:31]
	v_mfma_f32_16x16x32_bf16 v[28:31], v[158:161], v[196:199], v[28:31]
	v_mfma_f32_16x16x32_bf16 v[20:23], v[158:161], v[204:207], v[20:23]
	v_mfma_f32_16x16x32_bf16 v[20:23], v[162:165], v[208:211], v[20:23]
	v_mfma_f32_16x16x32_bf16 v[24:27], v[154:157], v[208:211], v[24:27]
	v_mfma_f32_16x16x32_bf16 v[24:27], v[150:153], v[204:207], v[24:27]
	s_setprio 0
	s_barrier
	s_add_i32 s56, s56, s13
	v_lshl_add_u64 v[212:213], s[42:43], 0, v[32:33]
	s_mov_b32 m0, s56
	ds_read_b128 v[166:169], v191 offset:16384
	ds_read_b128 v[180:183], v191 offset:17408
	ds_read_b128 v[184:187], v191 offset:18432
	ds_read_b128 v[192:195], v191 offset:19456
	ds_read_b128 v[196:199], v191 offset:20480
	ds_read_b128 v[200:203], v191 offset:21504
	ds_read_b128 v[204:207], v191 offset:22528
	ds_read_b128 v[208:211], v191 offset:23552
	global_load_lds_dwordx4 v[212:213], off
	s_add_i32 m0, s56, 0x2000
	s_add_u32 s56, s42, 0x80000
	v_lshl_add_u64 v[214:215], s[42:43], 0, v[174:175]
	s_addc_u32 s57, s43, 0
	s_add_i32 s58, s58, s13
	global_load_lds_dwordx4 v[214:215], off
	s_mov_b32 m0, s58
	v_lshl_add_u64 v[220:221], s[28:29], 0, v[172:173]
	global_load_lds_dwordx4 v32, s[56:57]
	s_add_i32 m0, s58, 0x2000
	s_nop 0
	global_load_lds_dwordx4 v174, s[56:57]
	v_lshl_add_u64 v[216:217], s[28:29], 0, v[170:171]
	s_mov_b32 m0, s24
	s_nop 0
	global_load_lds_dwordx4 v[216:217], off
	s_mov_b32 m0, s25
	s_nop 0
	global_load_lds_dwordx4 v[220:221], off
	s_waitcnt vmcnt(8)
	s_waitcnt lgkmcnt(0)
	s_barrier
	s_setprio 1
	s_waitcnt lgkmcnt(0)
	v_mfma_f32_16x16x32_bf16 v[16:19], v[134:137], v[166:169], v[16:19]
	v_mfma_f32_16x16x32_bf16 v[16:19], v[138:141], v[180:183], v[16:19]
	v_mfma_f32_16x16x32_bf16 v[12:15], v[146:149], v[180:183], v[12:15]
	v_mfma_f32_16x16x32_bf16 v[12:15], v[142:145], v[166:169], v[12:15]
	v_mfma_f32_16x16x32_bf16 v[4:7], v[142:145], v[184:187], v[4:7]
	v_mfma_f32_16x16x32_bf16 v[4:7], v[146:149], v[192:195], v[4:7]
	v_mfma_f32_16x16x32_bf16 v[8:11], v[138:141], v[192:195], v[8:11]
	v_mfma_f32_16x16x32_bf16 v[8:11], v[134:137], v[184:187], v[8:11]
	v_mfma_f32_16x16x32_bf16 v[0:3], v[134:137], v[196:199], v[0:3]
	v_mfma_f32_16x16x32_bf16 v[0:3], v[138:141], v[200:203], v[0:3]
	v_mfma_f32_16x16x32_bf16 v[86:89], v[146:149], v[200:203], v[86:89]
	v_mfma_f32_16x16x32_bf16 v[86:89], v[142:145], v[196:199], v[86:89]
	v_mfma_f32_16x16x32_bf16 v[94:97], v[142:145], v[204:207], v[94:97]
	v_mfma_f32_16x16x32_bf16 v[94:97], v[146:149], v[208:211], v[94:97]
	v_mfma_f32_16x16x32_bf16 v[90:93], v[138:141], v[208:211], v[90:93]
	v_mfma_f32_16x16x32_bf16 v[90:93], v[134:137], v[204:207], v[90:93]
	s_setprio 0
	s_setprio 1
	v_mfma_f32_16x16x32_bf16 v[98:101], v[150:153], v[166:169], v[98:101]
	v_mfma_f32_16x16x32_bf16 v[98:101], v[154:157], v[180:183], v[98:101]
	v_mfma_f32_16x16x32_bf16 v[102:105], v[162:165], v[180:183], v[102:105]
	v_mfma_f32_16x16x32_bf16 v[102:105], v[158:161], v[166:169], v[102:105]
	v_mfma_f32_16x16x32_bf16 v[110:113], v[158:161], v[184:187], v[110:113]
	v_mfma_f32_16x16x32_bf16 v[110:113], v[162:165], v[192:195], v[110:113]
	v_mfma_f32_16x16x32_bf16 v[106:109], v[154:157], v[192:195], v[106:109]
	v_mfma_f32_16x16x32_bf16 v[106:109], v[150:153], v[184:187], v[106:109]
	v_mfma_f32_16x16x32_bf16 v[114:117], v[150:153], v[196:199], v[114:117]
	v_mfma_f32_16x16x32_bf16 v[114:117], v[154:157], v[200:203], v[114:117]
	v_mfma_f32_16x16x32_bf16 v[118:121], v[162:165], v[200:203], v[118:121]
	v_mfma_f32_16x16x32_bf16 v[118:121], v[158:161], v[196:199], v[118:121]
	v_mfma_f32_16x16x32_bf16 v[126:129], v[158:161], v[204:207], v[126:129]
	v_mfma_f32_16x16x32_bf16 v[126:129], v[162:165], v[208:211], v[126:129]
	v_mfma_f32_16x16x32_bf16 v[122:125], v[154:157], v[208:211], v[122:125]
	v_mfma_f32_16x16x32_bf16 v[122:125], v[150:153], v[204:207], v[122:125]
	s_setprio 0
	s_barrier
	s_add_i32 s56, 0, 0x18000
	s_add_i32 s57, 0, 0x1c000
	v_add_u32_e32 v146, s56, v190
	v_add_u32_e32 v162, s57, v190
	ds_read_b128 v[134:137], v146
	ds_read_b128 v[138:141], v146 offset:1024
	ds_read_b128 v[142:145], v146 offset:2048
	ds_read_b128 v[146:149], v146 offset:3072
	ds_read_b128 v[150:153], v162
	ds_read_b128 v[154:157], v162 offset:1024
	ds_read_b128 v[158:161], v162 offset:2048
	ds_read_b128 v[162:165], v162 offset:3072
	s_add_u32 s28, s28, 0x80000
	s_addc_u32 s29, s29, 0
	s_mov_b32 m0, s33
	ds_read_b128 v[166:169], v191 offset:32768
	ds_read_b128 v[180:183], v191 offset:33792
	ds_read_b128 v[184:187], v191 offset:34816
	ds_read_b128 v[192:195], v191 offset:35840
	ds_read_b128 v[196:199], v191 offset:36864
	ds_read_b128 v[200:203], v191 offset:37888
	ds_read_b128 v[204:207], v191 offset:38912
	ds_read_b128 v[208:211], v191 offset:39936
	global_load_lds_dwordx4 v170, s[28:29]
	s_mov_b32 m0, s36
	s_nop 0
	global_load_lds_dwordx4 v172, s[28:29]
	s_waitcnt vmcnt(8)
	s_waitcnt lgkmcnt(0)
	s_barrier
	s_setprio 1
	s_waitcnt lgkmcnt(0)
	v_mfma_f32_16x16x32_bf16 v[82:85], v[134:137], v[166:169], v[82:85]
	v_mfma_f32_16x16x32_bf16 v[82:85], v[138:141], v[180:183], v[82:85]
	v_mfma_f32_16x16x32_bf16 v[78:81], v[146:149], v[180:183], v[78:81]
	v_mfma_f32_16x16x32_bf16 v[78:81], v[142:145], v[166:169], v[78:81]
	v_mfma_f32_16x16x32_bf16 v[70:73], v[142:145], v[184:187], v[70:73]
	v_mfma_f32_16x16x32_bf16 v[70:73], v[146:149], v[192:195], v[70:73]
	v_mfma_f32_16x16x32_bf16 v[74:77], v[138:141], v[192:195], v[74:77]
	v_mfma_f32_16x16x32_bf16 v[74:77], v[134:137], v[184:187], v[74:77]
	v_mfma_f32_16x16x32_bf16 v[66:69], v[134:137], v[196:199], v[66:69]
	v_mfma_f32_16x16x32_bf16 v[66:69], v[138:141], v[200:203], v[66:69]
	v_mfma_f32_16x16x32_bf16 v[62:65], v[146:149], v[200:203], v[62:65]
	v_mfma_f32_16x16x32_bf16 v[62:65], v[142:145], v[196:199], v[62:65]
	v_mfma_f32_16x16x32_bf16 v[54:57], v[142:145], v[204:207], v[54:57]
	v_mfma_f32_16x16x32_bf16 v[54:57], v[146:149], v[208:211], v[54:57]
	v_mfma_f32_16x16x32_bf16 v[58:61], v[138:141], v[208:211], v[58:61]
	v_mfma_f32_16x16x32_bf16 v[58:61], v[134:137], v[204:207], v[58:61]
	s_setprio 0
	s_setprio 1
	v_mfma_f32_16x16x32_bf16 v[50:53], v[150:153], v[166:169], v[50:53]
	v_mfma_f32_16x16x32_bf16 v[50:53], v[154:157], v[180:183], v[50:53]
	v_mfma_f32_16x16x32_bf16 v[46:49], v[162:165], v[180:183], v[46:49]
	v_mfma_f32_16x16x32_bf16 v[46:49], v[158:161], v[166:169], v[46:49]
	v_mfma_f32_16x16x32_bf16 v[38:41], v[158:161], v[184:187], v[38:41]
	v_mfma_f32_16x16x32_bf16 v[38:41], v[162:165], v[192:195], v[38:41]
	v_mfma_f32_16x16x32_bf16 v[42:45], v[154:157], v[192:195], v[42:45]
	v_mfma_f32_16x16x32_bf16 v[42:45], v[150:153], v[184:187], v[42:45]
	v_mfma_f32_16x16x32_bf16 v[34:37], v[150:153], v[196:199], v[34:37]
	v_mfma_f32_16x16x32_bf16 v[34:37], v[154:157], v[200:203], v[34:37]
	v_mfma_f32_16x16x32_bf16 v[28:31], v[162:165], v[200:203], v[28:31]
	v_mfma_f32_16x16x32_bf16 v[28:31], v[158:161], v[196:199], v[28:31]
	v_mfma_f32_16x16x32_bf16 v[20:23], v[158:161], v[204:207], v[20:23]
	v_mfma_f32_16x16x32_bf16 v[20:23], v[162:165], v[208:211], v[20:23]
	v_mfma_f32_16x16x32_bf16 v[24:27], v[154:157], v[208:211], v[24:27]
	v_mfma_f32_16x16x32_bf16 v[24:27], v[150:153], v[204:207], v[24:27]
	s_setprio 0
	s_barrier
	s_add_i32 s28, s56, s13
	v_lshl_add_u64 v[212:213], v[212:213], 0, s[34:35]
	s_mov_b32 m0, s28
	ds_read_b128 v[166:169], v191 offset:49152
	ds_read_b128 v[180:183], v191 offset:50176
	ds_read_b128 v[184:187], v191 offset:51200
	ds_read_b128 v[192:195], v191 offset:52224
	ds_read_b128 v[196:199], v191 offset:53248
	ds_read_b128 v[200:203], v191 offset:54272
	ds_read_b128 v[204:207], v191 offset:55296
	ds_read_b128 v[208:211], v191 offset:56320
	global_load_lds_dwordx4 v[212:213], off
	s_add_i32 m0, s28, 0x2000
	s_add_u32 s28, s42, 0x80080
	v_lshl_add_u64 v[212:213], v[214:215], 0, s[34:35]
	s_addc_u32 s29, s43, 0
	s_add_i32 s42, s57, s13
	global_load_lds_dwordx4 v[212:213], off
	s_mov_b32 m0, s42
	s_nop 0
	global_load_lds_dwordx4 v32, s[28:29]
	s_add_i32 m0, s42, 0x2000
	s_nop 0
	global_load_lds_dwordx4 v174, s[28:29]
	v_lshl_add_u64 v[212:213], v[216:217], 0, s[34:35]
	s_mov_b32 m0, s45
	s_nop 0
	global_load_lds_dwordx4 v[212:213], off
	v_lshl_add_u64 v[212:213], v[220:221], 0, s[34:35]
	s_mov_b32 m0, s46
	s_nop 0
	global_load_lds_dwordx4 v[212:213], off
	s_waitcnt vmcnt(8)
	s_waitcnt lgkmcnt(0)
	s_barrier
	s_setprio 1
	s_waitcnt lgkmcnt(0)
	v_mfma_f32_16x16x32_bf16 v[16:19], v[134:137], v[166:169], v[16:19]
	v_mfma_f32_16x16x32_bf16 v[16:19], v[138:141], v[180:183], v[16:19]
	v_mfma_f32_16x16x32_bf16 v[12:15], v[146:149], v[180:183], v[12:15]
	v_mfma_f32_16x16x32_bf16 v[12:15], v[142:145], v[166:169], v[12:15]
	v_mfma_f32_16x16x32_bf16 v[4:7], v[142:145], v[184:187], v[4:7]
	v_mfma_f32_16x16x32_bf16 v[4:7], v[146:149], v[192:195], v[4:7]
	v_mfma_f32_16x16x32_bf16 v[8:11], v[138:141], v[192:195], v[8:11]
	v_mfma_f32_16x16x32_bf16 v[8:11], v[134:137], v[184:187], v[8:11]
	v_mfma_f32_16x16x32_bf16 v[0:3], v[134:137], v[196:199], v[0:3]
	v_mfma_f32_16x16x32_bf16 v[0:3], v[138:141], v[200:203], v[0:3]
	v_mfma_f32_16x16x32_bf16 v[86:89], v[146:149], v[200:203], v[86:89]
	v_mfma_f32_16x16x32_bf16 v[86:89], v[142:145], v[196:199], v[86:89]
	v_mfma_f32_16x16x32_bf16 v[94:97], v[142:145], v[204:207], v[94:97]
	v_mfma_f32_16x16x32_bf16 v[94:97], v[146:149], v[208:211], v[94:97]
	v_mfma_f32_16x16x32_bf16 v[90:93], v[138:141], v[208:211], v[90:93]
	v_mfma_f32_16x16x32_bf16 v[90:93], v[134:137], v[204:207], v[90:93]
	s_setprio 0
	s_setprio 1
	v_mfma_f32_16x16x32_bf16 v[98:101], v[150:153], v[166:169], v[98:101]
	v_mfma_f32_16x16x32_bf16 v[98:101], v[154:157], v[180:183], v[98:101]
	v_mfma_f32_16x16x32_bf16 v[102:105], v[162:165], v[180:183], v[102:105]
	v_mfma_f32_16x16x32_bf16 v[102:105], v[158:161], v[166:169], v[102:105]
	v_mfma_f32_16x16x32_bf16 v[110:113], v[158:161], v[184:187], v[110:113]
	v_mfma_f32_16x16x32_bf16 v[110:113], v[162:165], v[192:195], v[110:113]
	v_mfma_f32_16x16x32_bf16 v[106:109], v[154:157], v[192:195], v[106:109]
	v_mfma_f32_16x16x32_bf16 v[106:109], v[150:153], v[184:187], v[106:109]
	v_mfma_f32_16x16x32_bf16 v[114:117], v[150:153], v[196:199], v[114:117]
	v_mfma_f32_16x16x32_bf16 v[114:117], v[154:157], v[200:203], v[114:117]
	v_mfma_f32_16x16x32_bf16 v[118:121], v[162:165], v[200:203], v[118:121]
	v_mfma_f32_16x16x32_bf16 v[118:121], v[158:161], v[196:199], v[118:121]
	v_mfma_f32_16x16x32_bf16 v[126:129], v[158:161], v[204:207], v[126:129]
	v_mfma_f32_16x16x32_bf16 v[126:129], v[162:165], v[208:211], v[126:129]
	v_mfma_f32_16x16x32_bf16 v[122:125], v[154:157], v[208:211], v[122:125]
	v_mfma_f32_16x16x32_bf16 v[122:125], v[150:153], v[204:207], v[122:125]
	s_setprio 0
	s_barrier
	s_add_i32 s55, s55, 2
	s_add_u32 s40, s40, 0x100
	s_addc_u32 s41, s41, 0
	s_cmp_gt_u32 s55, 29
	s_cbranch_scc0 .LBB0_685
	s_and_b64 vcc, exec, s[18:19]
	s_cbranch_vccz .LBB0_688
	s_barrier

.LBB0_755:
	s_add_u32 s6, s4, 0x100
	s_addc_u32 s7, s5, 0
	s_add_i32 s52, 0, 0x10000
	s_cmpk_eq_i32 s51, 0x54
	s_cselect_b32 s29, s23, s7
	s_cselect_b32 s28, s22, s6
	s_cselect_b32 s31, s27, s50
	s_cselect_b32 s30, s26, s33
	s_add_i32 s53, 0, 0x14000
	v_add_u32_e32 v142, s52, v242
	v_add_u32_e32 v158, s53, v242
	ds_read_b128 v[130:133], v142
	ds_read_b128 v[134:137], v142 offset:1024
	ds_read_b128 v[138:141], v142 offset:2048
	ds_read_b128 v[142:145], v142 offset:3072
	ds_read_b128 v[146:149], v158
	ds_read_b128 v[150:153], v158 offset:1024
	ds_read_b128 v[154:157], v158 offset:2048
	ds_read_b128 v[158:161], v158 offset:3072
	s_add_i32 m0, s36, 0xc000
	ds_read_b128 v[162:165], v243
	ds_read_b128 v[166:169], v243 offset:1024
	ds_read_b128 v[170:173], v243 offset:2048
	ds_read_b128 v[174:177], v243 offset:3072
	ds_read_b128 v[178:181], v243 offset:4096
	ds_read_b128 v[182:185], v243 offset:5120
	ds_read_b128 v[186:189], v243 offset:6144
	ds_read_b128 v[190:193], v243 offset:7168
	global_load_lds_dwordx4 v202, s[4:5]
	s_add_i32 m0, s36, 0xe000
	s_nop 0
	global_load_lds_dwordx4 v204, s[4:5]
	s_waitcnt vmcnt(8)
	s_waitcnt lgkmcnt(0)
	s_barrier
	s_setprio 1
	s_waitcnt lgkmcnt(0)
	v_mfma_f32_16x16x32_bf16 v[126:129], v[130:133], v[162:165], v[126:129]
	v_mfma_f32_16x16x32_bf16 v[126:129], v[134:137], v[166:169], v[126:129]
	v_mfma_f32_16x16x32_bf16 v[122:125], v[142:145], v[166:169], v[122:125]
	v_mfma_f32_16x16x32_bf16 v[122:125], v[138:141], v[162:165], v[122:125]
	v_mfma_f32_16x16x32_bf16 v[106:109], v[138:141], v[170:173], v[106:109]
	v_mfma_f32_16x16x32_bf16 v[106:109], v[142:145], v[174:177], v[106:109]
	v_mfma_f32_16x16x32_bf16 v[110:113], v[134:137], v[174:177], v[110:113]
	v_mfma_f32_16x16x32_bf16 v[110:113], v[130:133], v[170:173], v[110:113]
	v_mfma_f32_16x16x32_bf16 v[94:97], v[130:133], v[178:181], v[94:97]
	v_mfma_f32_16x16x32_bf16 v[94:97], v[134:137], v[182:185], v[94:97]
	v_mfma_f32_16x16x32_bf16 v[90:93], v[142:145], v[182:185], v[90:93]
	v_mfma_f32_16x16x32_bf16 v[90:93], v[138:141], v[178:181], v[90:93]
	v_mfma_f32_16x16x32_bf16 v[74:77], v[138:141], v[186:189], v[74:77]
	v_mfma_f32_16x16x32_bf16 v[74:77], v[142:145], v[190:193], v[74:77]
	v_mfma_f32_16x16x32_bf16 v[78:81], v[134:137], v[190:193], v[78:81]
	v_mfma_f32_16x16x32_bf16 v[78:81], v[130:133], v[186:189], v[78:81]
	s_setprio 0
	s_setprio 1
	v_mfma_f32_16x16x32_bf16 v[118:121], v[146:149], v[162:165], v[118:121]
	v_mfma_f32_16x16x32_bf16 v[118:121], v[150:153], v[166:169], v[118:121]
	v_mfma_f32_16x16x32_bf16 v[114:117], v[158:161], v[166:169], v[114:117]
	v_mfma_f32_16x16x32_bf16 v[114:117], v[154:157], v[162:165], v[114:117]
	v_mfma_f32_16x16x32_bf16 v[98:101], v[154:157], v[170:173], v[98:101]
	v_mfma_f32_16x16x32_bf16 v[98:101], v[158:161], v[174:177], v[98:101]
	v_mfma_f32_16x16x32_bf16 v[102:105], v[150:153], v[174:177], v[102:105]
	v_mfma_f32_16x16x32_bf16 v[102:105], v[146:149], v[170:173], v[102:105]
	v_mfma_f32_16x16x32_bf16 v[86:89], v[146:149], v[178:181], v[86:89]
	v_mfma_f32_16x16x32_bf16 v[86:89], v[150:153], v[182:185], v[86:89]
	v_mfma_f32_16x16x32_bf16 v[82:85], v[158:161], v[182:185], v[82:85]
	v_mfma_f32_16x16x32_bf16 v[82:85], v[154:157], v[178:181], v[82:85]
	v_mfma_f32_16x16x32_bf16 v[66:69], v[154:157], v[186:189], v[66:69]
	v_mfma_f32_16x16x32_bf16 v[66:69], v[158:161], v[190:193], v[66:69]
	v_mfma_f32_16x16x32_bf16 v[70:73], v[150:153], v[190:193], v[70:73]
	v_mfma_f32_16x16x32_bf16 v[70:73], v[146:149], v[186:189], v[70:73]
	s_setprio 0
	s_barrier
	s_add_i32 s4, s52, s1
	v_lshl_add_u64 v[194:195], s[30:31], 0, v[32:33]
	s_mov_b32 m0, s4
	ds_read_b128 v[162:165], v243 offset:16384
	ds_read_b128 v[166:169], v243 offset:17408
	ds_read_b128 v[170:173], v243 offset:18432
	ds_read_b128 v[174:177], v243 offset:19456
	ds_read_b128 v[178:181], v243 offset:20480
	ds_read_b128 v[182:185], v243 offset:21504
	ds_read_b128 v[186:189], v243 offset:22528
	ds_read_b128 v[190:193], v243 offset:23552
	global_load_lds_dwordx4 v[194:195], off
	s_add_i32 m0, s4, 0x2000
	s_add_u32 s4, s30, 0x160000
	v_lshl_add_u64 v[206:207], s[30:31], 0, v[200:201]
	s_addc_u32 s5, s31, 0
	s_add_i32 s52, s53, s1
	global_load_lds_dwordx4 v[206:207], off
	s_mov_b32 m0, s52
	v_lshl_add_u64 v[210:211], s[28:29], 0, v[198:199]
	global_load_lds_dwordx4 v32, s[4:5]
	s_add_i32 m0, s52, 0x2000
	s_nop 0
	global_load_lds_dwordx4 v200, s[4:5]
	v_lshl_add_u64 v[208:209], s[28:29], 0, v[196:197]
	s_mov_b32 m0, s36
	s_nop 0
	global_load_lds_dwordx4 v[208:209], off
	s_mov_b32 m0, s38
	s_nop 0
	global_load_lds_dwordx4 v[210:211], off
	s_waitcnt vmcnt(8)
	s_waitcnt lgkmcnt(0)
	s_barrier
	s_setprio 1
	s_waitcnt lgkmcnt(0)
	v_mfma_f32_16x16x32_bf16 v[62:65], v[130:133], v[162:165], v[62:65]
	v_mfma_f32_16x16x32_bf16 v[62:65], v[134:137], v[166:169], v[62:65]
	v_mfma_f32_16x16x32_bf16 v[58:61], v[142:145], v[166:169], v[58:61]
	v_mfma_f32_16x16x32_bf16 v[58:61], v[138:141], v[162:165], v[58:61]
	v_mfma_f32_16x16x32_bf16 v[42:45], v[138:141], v[170:173], v[42:45]
	v_mfma_f32_16x16x32_bf16 v[42:45], v[142:145], v[174:177], v[42:45]
	v_mfma_f32_16x16x32_bf16 v[46:49], v[134:137], v[174:177], v[46:49]
	v_mfma_f32_16x16x32_bf16 v[46:49], v[130:133], v[170:173], v[46:49]
	v_mfma_f32_16x16x32_bf16 v[28:31], v[130:133], v[178:181], v[28:31]
	v_mfma_f32_16x16x32_bf16 v[28:31], v[134:137], v[182:185], v[28:31]
	v_mfma_f32_16x16x32_bf16 v[24:27], v[142:145], v[182:185], v[24:27]
	v_mfma_f32_16x16x32_bf16 v[24:27], v[138:141], v[178:181], v[24:27]
	v_mfma_f32_16x16x32_bf16 v[8:11], v[138:141], v[186:189], v[8:11]
	v_mfma_f32_16x16x32_bf16 v[8:11], v[142:145], v[190:193], v[8:11]
	v_mfma_f32_16x16x32_bf16 v[12:15], v[134:137], v[190:193], v[12:15]
	v_mfma_f32_16x16x32_bf16 v[12:15], v[130:133], v[186:189], v[12:15]
	s_setprio 0
	s_setprio 1
	v_mfma_f32_16x16x32_bf16 v[54:57], v[146:149], v[162:165], v[54:57]
	v_mfma_f32_16x16x32_bf16 v[54:57], v[150:153], v[166:169], v[54:57]
	v_mfma_f32_16x16x32_bf16 v[50:53], v[158:161], v[166:169], v[50:53]
	v_mfma_f32_16x16x32_bf16 v[50:53], v[154:157], v[162:165], v[50:53]
	v_mfma_f32_16x16x32_bf16 v[34:37], v[154:157], v[170:173], v[34:37]
	v_mfma_f32_16x16x32_bf16 v[34:37], v[158:161], v[174:177], v[34:37]
	v_mfma_f32_16x16x32_bf16 v[38:41], v[150:153], v[174:177], v[38:41]
	v_mfma_f32_16x16x32_bf16 v[38:41], v[146:149], v[170:173], v[38:41]
	v_mfma_f32_16x16x32_bf16 v[20:23], v[146:149], v[178:181], v[20:23]
	v_mfma_f32_16x16x32_bf16 v[20:23], v[150:153], v[182:185], v[20:23]
	v_mfma_f32_16x16x32_bf16 v[16:19], v[158:161], v[182:185], v[16:19]
	v_mfma_f32_16x16x32_bf16 v[16:19], v[154:157], v[178:181], v[16:19]
	v_mfma_f32_16x16x32_bf16 v[0:3], v[154:157], v[186:189], v[0:3]
	v_mfma_f32_16x16x32_bf16 v[0:3], v[158:161], v[190:193], v[0:3]
	v_mfma_f32_16x16x32_bf16 v[4:7], v[150:153], v[190:193], v[4:7]
	v_mfma_f32_16x16x32_bf16 v[4:7], v[146:149], v[186:189], v[4:7]
	s_setprio 0
	s_barrier
	s_add_i32 s52, 0, 0x18000
	s_add_i32 s53, 0, 0x1c000
	v_add_u32_e32 v142, s52, v242
	v_add_u32_e32 v158, s53, v242
	ds_read_b128 v[130:133], v142
	ds_read_b128 v[134:137], v142 offset:1024
	ds_read_b128 v[138:141], v142 offset:2048
	ds_read_b128 v[142:145], v142 offset:3072
	ds_read_b128 v[146:149], v158
	ds_read_b128 v[150:153], v158 offset:1024
	ds_read_b128 v[154:157], v158 offset:2048
	ds_read_b128 v[158:161], v158 offset:3072
	s_add_u32 s4, s28, 0x160000
	s_addc_u32 s5, s29, 0
	s_mov_b32 m0, s39
	ds_read_b128 v[162:165], v243 offset:32768
	ds_read_b128 v[166:169], v243 offset:33792
	ds_read_b128 v[170:173], v243 offset:34816
	ds_read_b128 v[174:177], v243 offset:35840
	ds_read_b128 v[178:181], v243 offset:36864
	ds_read_b128 v[182:185], v243 offset:37888
	ds_read_b128 v[186:189], v243 offset:38912
	ds_read_b128 v[190:193], v243 offset:39936
	global_load_lds_dwordx4 v196, s[4:5]
	s_mov_b32 m0, s42
	s_nop 0
	global_load_lds_dwordx4 v198, s[4:5]
	s_waitcnt vmcnt(8)
	s_waitcnt lgkmcnt(0)
	s_barrier
	s_setprio 1
	s_waitcnt lgkmcnt(0)
	v_mfma_f32_16x16x32_bf16 v[126:129], v[130:133], v[162:165], v[126:129]
	v_mfma_f32_16x16x32_bf16 v[126:129], v[134:137], v[166:169], v[126:129]
	v_mfma_f32_16x16x32_bf16 v[122:125], v[142:145], v[166:169], v[122:125]
	v_mfma_f32_16x16x32_bf16 v[122:125], v[138:141], v[162:165], v[122:125]
	v_mfma_f32_16x16x32_bf16 v[106:109], v[138:141], v[170:173], v[106:109]
	v_mfma_f32_16x16x32_bf16 v[106:109], v[142:145], v[174:177], v[106:109]
	v_mfma_f32_16x16x32_bf16 v[110:113], v[134:137], v[174:177], v[110:113]
	v_mfma_f32_16x16x32_bf16 v[110:113], v[130:133], v[170:173], v[110:113]
	v_mfma_f32_16x16x32_bf16 v[94:97], v[130:133], v[178:181], v[94:97]
	v_mfma_f32_16x16x32_bf16 v[94:97], v[134:137], v[182:185], v[94:97]
	v_mfma_f32_16x16x32_bf16 v[90:93], v[142:145], v[182:185], v[90:93]
	v_mfma_f32_16x16x32_bf16 v[90:93], v[138:141], v[178:181], v[90:93]
	v_mfma_f32_16x16x32_bf16 v[74:77], v[138:141], v[186:189], v[74:77]
	v_mfma_f32_16x16x32_bf16 v[74:77], v[142:145], v[190:193], v[74:77]
	v_mfma_f32_16x16x32_bf16 v[78:81], v[134:137], v[190:193], v[78:81]
	v_mfma_f32_16x16x32_bf16 v[78:81], v[130:133], v[186:189], v[78:81]
	s_setprio 0
	s_setprio 1
	v_mfma_f32_16x16x32_bf16 v[118:121], v[146:149], v[162:165], v[118:121]
	v_mfma_f32_16x16x32_bf16 v[118:121], v[150:153], v[166:169], v[118:121]
	v_mfma_f32_16x16x32_bf16 v[114:117], v[158:161], v[166:169], v[114:117]
	v_mfma_f32_16x16x32_bf16 v[114:117], v[154:157], v[162:165], v[114:117]
	v_mfma_f32_16x16x32_bf16 v[98:101], v[154:157], v[170:173], v[98:101]
	v_mfma_f32_16x16x32_bf16 v[98:101], v[158:161], v[174:177], v[98:101]
	v_mfma_f32_16x16x32_bf16 v[102:105], v[150:153], v[174:177], v[102:105]
	v_mfma_f32_16x16x32_bf16 v[102:105], v[146:149], v[170:173], v[102:105]
	v_mfma_f32_16x16x32_bf16 v[86:89], v[146:149], v[178:181], v[86:89]
	v_mfma_f32_16x16x32_bf16 v[86:89], v[150:153], v[182:185], v[86:89]
	v_mfma_f32_16x16x32_bf16 v[82:85], v[158:161], v[182:185], v[82:85]
	v_mfma_f32_16x16x32_bf16 v[82:85], v[154:157], v[178:181], v[82:85]
	v_mfma_f32_16x16x32_bf16 v[66:69], v[154:157], v[186:189], v[66:69]
	v_mfma_f32_16x16x32_bf16 v[66:69], v[158:161], v[190:193], v[66:69]
	v_mfma_f32_16x16x32_bf16 v[70:73], v[150:153], v[190:193], v[70:73]
	v_mfma_f32_16x16x32_bf16 v[70:73], v[146:149], v[186:189], v[70:73]
	s_setprio 0
	s_barrier
	s_add_i32 s4, s52, s1
	v_lshl_add_u64 v[194:195], v[194:195], 0, s[34:35]
	s_mov_b32 m0, s4
	ds_read_b128 v[162:165], v243 offset:49152
	ds_read_b128 v[166:169], v243 offset:50176
	ds_read_b128 v[170:173], v243 offset:51200
	ds_read_b128 v[174:177], v243 offset:52224
	ds_read_b128 v[178:181], v243 offset:53248
	ds_read_b128 v[182:185], v243 offset:54272
	ds_read_b128 v[186:189], v243 offset:55296
	ds_read_b128 v[190:193], v243 offset:56320
	global_load_lds_dwordx4 v[194:195], off
	s_add_i32 m0, s4, 0x2000
	s_add_u32 s4, s30, 0x160080
	v_lshl_add_u64 v[194:195], v[206:207], 0, s[34:35]
	s_addc_u32 s5, s31, 0
	s_add_i32 s28, s53, s1
	global_load_lds_dwordx4 v[194:195], off
	s_mov_b32 m0, s28
	s_nop 0
	global_load_lds_dwordx4 v32, s[4:5]
	s_add_i32 m0, s28, 0x2000
	s_nop 0
	global_load_lds_dwordx4 v200, s[4:5]
	v_lshl_add_u64 v[194:195], v[208:209], 0, s[34:35]
	s_mov_b32 m0, s44
	s_nop 0
	global_load_lds_dwordx4 v[194:195], off
	v_lshl_add_u64 v[194:195], v[210:211], 0, s[34:35]
	s_mov_b32 m0, s45
	s_nop 0
	global_load_lds_dwordx4 v[194:195], off
	s_waitcnt vmcnt(8)
	s_waitcnt lgkmcnt(0)
	s_barrier
	s_setprio 1
	s_waitcnt lgkmcnt(0)
	v_mfma_f32_16x16x32_bf16 v[62:65], v[130:133], v[162:165], v[62:65]
	v_mfma_f32_16x16x32_bf16 v[62:65], v[134:137], v[166:169], v[62:65]
	v_mfma_f32_16x16x32_bf16 v[58:61], v[142:145], v[166:169], v[58:61]
	v_mfma_f32_16x16x32_bf16 v[58:61], v[138:141], v[162:165], v[58:61]
	v_mfma_f32_16x16x32_bf16 v[42:45], v[138:141], v[170:173], v[42:45]
	v_mfma_f32_16x16x32_bf16 v[42:45], v[142:145], v[174:177], v[42:45]
	v_mfma_f32_16x16x32_bf16 v[46:49], v[134:137], v[174:177], v[46:49]
	v_mfma_f32_16x16x32_bf16 v[46:49], v[130:133], v[170:173], v[46:49]
	v_mfma_f32_16x16x32_bf16 v[28:31], v[130:133], v[178:181], v[28:31]
	v_mfma_f32_16x16x32_bf16 v[28:31], v[134:137], v[182:185], v[28:31]
	v_mfma_f32_16x16x32_bf16 v[24:27], v[142:145], v[182:185], v[24:27]
	v_mfma_f32_16x16x32_bf16 v[24:27], v[138:141], v[178:181], v[24:27]
	v_mfma_f32_16x16x32_bf16 v[8:11], v[138:141], v[186:189], v[8:11]
	v_mfma_f32_16x16x32_bf16 v[8:11], v[142:145], v[190:193], v[8:11]
	v_mfma_f32_16x16x32_bf16 v[12:15], v[134:137], v[190:193], v[12:15]
	v_mfma_f32_16x16x32_bf16 v[12:15], v[130:133], v[186:189], v[12:15]
	s_setprio 0
	s_setprio 1
	v_mfma_f32_16x16x32_bf16 v[54:57], v[146:149], v[162:165], v[54:57]
	v_mfma_f32_16x16x32_bf16 v[54:57], v[150:153], v[166:169], v[54:57]
	v_mfma_f32_16x16x32_bf16 v[50:53], v[158:161], v[166:169], v[50:53]
	v_mfma_f32_16x16x32_bf16 v[50:53], v[154:157], v[162:165], v[50:53]
	v_mfma_f32_16x16x32_bf16 v[34:37], v[154:157], v[170:173], v[34:37]
	v_mfma_f32_16x16x32_bf16 v[34:37], v[158:161], v[174:177], v[34:37]
	v_mfma_f32_16x16x32_bf16 v[38:41], v[150:153], v[174:177], v[38:41]
	v_mfma_f32_16x16x32_bf16 v[38:41], v[146:149], v[170:173], v[38:41]
	v_mfma_f32_16x16x32_bf16 v[20:23], v[146:149], v[178:181], v[20:23]
	v_mfma_f32_16x16x32_bf16 v[20:23], v[150:153], v[182:185], v[20:23]
	v_mfma_f32_16x16x32_bf16 v[16:19], v[158:161], v[182:185], v[16:19]
	v_mfma_f32_16x16x32_bf16 v[16:19], v[154:157], v[178:181], v[16:19]
	v_mfma_f32_16x16x32_bf16 v[0:3], v[154:157], v[186:189], v[0:3]
	v_mfma_f32_16x16x32_bf16 v[0:3], v[158:161], v[190:193], v[0:3]
	v_mfma_f32_16x16x32_bf16 v[4:7], v[150:153], v[190:193], v[4:7]
	v_mfma_f32_16x16x32_bf16 v[4:7], v[146:149], v[186:189], v[4:7]
	s_setprio 0
	s_barrier
	s_add_i32 s51, s51, 2
	s_add_u32 s33, s33, 0x100
	s_addc_u32 s50, s50, 0
	s_cmpk_gt_u32 s51, 0x55
	s_mov_b64 s[4:5], s[6:7]
	s_cbranch_scc0 .LBB0_755
	s_and_b64 vcc, exec, s[18:19]
	s_cbranch_vccz .LBB0_758
	s_barrier

.LBB0_888:
	s_add_u32 s38, s16, s30
	s_addc_u32 s39, s17, s31
	s_add_u32 s38, s38, 0x100
	s_addc_u32 s39, s39, 0
	s_add_u32 s54, s50, s30
	s_addc_u32 s55, s51, s31
	s_add_i32 s56, 0, 0x10000
	s_cmpk_eq_i32 s30, 0xf00
	s_cselect_b32 s41, s29, s39
	s_cselect_b32 s40, s28, s38
	s_cselect_b32 s39, s21, s55
	s_cselect_b32 s38, s52, s54
	s_add_i32 s57, 0, 0x14000
	v_add_u32_e32 v146, s56, v178
	v_add_u32_e32 v172, s57, v178
	ds_read_b128 v[134:137], v146
	ds_read_b128 v[138:141], v146 offset:1024
	ds_read_b128 v[142:145], v146 offset:2048
	ds_read_b128 v[146:149], v146 offset:3072
	ds_read_b128 v[150:153], v172
	ds_read_b128 v[154:157], v172 offset:1024
	ds_read_b128 v[158:161], v172 offset:2048
	ds_read_b128 v[172:175], v172 offset:3072
	v_lshl_add_u64 v[212:213], v[130:131], 0, s[30:31]
	s_add_i32 m0, s24, 0xc000
	ds_read_b128 v[180:183], v179
	ds_read_b128 v[184:187], v179 offset:1024
	ds_read_b128 v[188:191], v179 offset:2048
	ds_read_b128 v[192:195], v179 offset:3072
	ds_read_b128 v[196:199], v179 offset:4096
	ds_read_b128 v[200:203], v179 offset:5120
	ds_read_b128 v[204:207], v179 offset:6144
	ds_read_b128 v[208:211], v179 offset:7168
	global_load_lds_dwordx4 v[212:213], off
	v_lshl_add_u64 v[212:213], v[132:133], 0, s[30:31]
	s_add_i32 m0, s24, 0xe000
	s_nop 0
	global_load_lds_dwordx4 v[212:213], off
	s_waitcnt vmcnt(8)
	s_waitcnt lgkmcnt(0)
	s_barrier
	s_setprio 1
	s_waitcnt lgkmcnt(0)
	v_mfma_f32_16x16x32_bf16 v[82:85], v[134:137], v[180:183], v[82:85]
	v_mfma_f32_16x16x32_bf16 v[82:85], v[138:141], v[184:187], v[82:85]
	v_mfma_f32_16x16x32_bf16 v[78:81], v[146:149], v[184:187], v[78:81]
	v_mfma_f32_16x16x32_bf16 v[78:81], v[142:145], v[180:183], v[78:81]
	v_mfma_f32_16x16x32_bf16 v[70:73], v[142:145], v[188:191], v[70:73]
	v_mfma_f32_16x16x32_bf16 v[70:73], v[146:149], v[192:195], v[70:73]
	v_mfma_f32_16x16x32_bf16 v[74:77], v[138:141], v[192:195], v[74:77]
	v_mfma_f32_16x16x32_bf16 v[74:77], v[134:137], v[188:191], v[74:77]
	v_mfma_f32_16x16x32_bf16 v[66:69], v[134:137], v[196:199], v[66:69]
	v_mfma_f32_16x16x32_bf16 v[66:69], v[138:141], v[200:203], v[66:69]
	v_mfma_f32_16x16x32_bf16 v[62:65], v[146:149], v[200:203], v[62:65]
	v_mfma_f32_16x16x32_bf16 v[62:65], v[142:145], v[196:199], v[62:65]
	v_mfma_f32_16x16x32_bf16 v[54:57], v[142:145], v[204:207], v[54:57]
	v_mfma_f32_16x16x32_bf16 v[54:57], v[146:149], v[208:211], v[54:57]
	v_mfma_f32_16x16x32_bf16 v[58:61], v[138:141], v[208:211], v[58:61]
	v_mfma_f32_16x16x32_bf16 v[58:61], v[134:137], v[204:207], v[58:61]
	s_setprio 0
	s_setprio 1
	v_mfma_f32_16x16x32_bf16 v[50:53], v[150:153], v[180:183], v[50:53]
	v_mfma_f32_16x16x32_bf16 v[50:53], v[154:157], v[184:187], v[50:53]
	v_mfma_f32_16x16x32_bf16 v[46:49], v[172:175], v[184:187], v[46:49]
	v_mfma_f32_16x16x32_bf16 v[46:49], v[158:161], v[180:183], v[46:49]
	v_mfma_f32_16x16x32_bf16 v[38:41], v[158:161], v[188:191], v[38:41]
	v_mfma_f32_16x16x32_bf16 v[38:41], v[172:175], v[192:195], v[38:41]
	v_mfma_f32_16x16x32_bf16 v[42:45], v[154:157], v[192:195], v[42:45]
	v_mfma_f32_16x16x32_bf16 v[42:45], v[150:153], v[188:191], v[42:45]
	v_mfma_f32_16x16x32_bf16 v[34:37], v[150:153], v[196:199], v[34:37]
	v_mfma_f32_16x16x32_bf16 v[34:37], v[154:157], v[200:203], v[34:37]
	v_mfma_f32_16x16x32_bf16 v[28:31], v[172:175], v[200:203], v[28:31]
	v_mfma_f32_16x16x32_bf16 v[28:31], v[158:161], v[196:199], v[28:31]
	v_mfma_f32_16x16x32_bf16 v[20:23], v[158:161], v[204:207], v[20:23]
	v_mfma_f32_16x16x32_bf16 v[20:23], v[172:175], v[208:211], v[20:23]
	v_mfma_f32_16x16x32_bf16 v[24:27], v[154:157], v[208:211], v[24:27]
	v_mfma_f32_16x16x32_bf16 v[24:27], v[150:153], v[204:207], v[24:27]
	s_setprio 0
	s_barrier
	s_add_i32 s54, s56, s13
	v_lshl_add_u64 v[212:213], s[38:39], 0, v[32:33]
	s_mov_b32 m0, s54
	ds_read_b128 v[180:183], v179 offset:16384
	ds_read_b128 v[184:187], v179 offset:17408
	ds_read_b128 v[188:191], v179 offset:18432
	ds_read_b128 v[192:195], v179 offset:19456
	ds_read_b128 v[196:199], v179 offset:20480
	ds_read_b128 v[200:203], v179 offset:21504
	ds_read_b128 v[204:207], v179 offset:22528
	ds_read_b128 v[208:211], v179 offset:23552
	global_load_lds_dwordx4 v[212:213], off
	s_add_i32 m0, s54, 0x2000
	s_add_u32 s54, s38, 0x80000
	v_lshl_add_u64 v[214:215], s[38:39], 0, v[166:167]
	s_addc_u32 s55, s39, 0
	s_add_i32 s56, s57, s13
	global_load_lds_dwordx4 v[214:215], off
	s_mov_b32 m0, s56
	v_lshl_add_u64 v[220:221], s[40:41], 0, v[164:165]
	global_load_lds_dwordx4 v32, s[54:55]
	s_add_i32 m0, s56, 0x2000
	s_nop 0
	global_load_lds_dwordx4 v166, s[54:55]
	v_lshl_add_u64 v[216:217], s[40:41], 0, v[162:163]
	s_mov_b32 m0, s24
	s_nop 0
	global_load_lds_dwordx4 v[216:217], off
	s_mov_b32 m0, s25
	s_nop 0
	global_load_lds_dwordx4 v[220:221], off
	s_waitcnt vmcnt(8)
	s_waitcnt lgkmcnt(0)
	s_barrier
	s_setprio 1
	s_waitcnt lgkmcnt(0)
	v_mfma_f32_16x16x32_bf16 v[16:19], v[134:137], v[180:183], v[16:19]
	v_mfma_f32_16x16x32_bf16 v[16:19], v[138:141], v[184:187], v[16:19]
	v_mfma_f32_16x16x32_bf16 v[12:15], v[146:149], v[184:187], v[12:15]
	v_mfma_f32_16x16x32_bf16 v[12:15], v[142:145], v[180:183], v[12:15]
	v_mfma_f32_16x16x32_bf16 v[4:7], v[142:145], v[188:191], v[4:7]
	v_mfma_f32_16x16x32_bf16 v[4:7], v[146:149], v[192:195], v[4:7]
	v_mfma_f32_16x16x32_bf16 v[8:11], v[138:141], v[192:195], v[8:11]
	v_mfma_f32_16x16x32_bf16 v[8:11], v[134:137], v[188:191], v[8:11]
	v_mfma_f32_16x16x32_bf16 v[0:3], v[134:137], v[196:199], v[0:3]
	v_mfma_f32_16x16x32_bf16 v[0:3], v[138:141], v[200:203], v[0:3]
	v_mfma_f32_16x16x32_bf16 v[86:89], v[146:149], v[200:203], v[86:89]
	v_mfma_f32_16x16x32_bf16 v[86:89], v[142:145], v[196:199], v[86:89]
	v_mfma_f32_16x16x32_bf16 v[94:97], v[142:145], v[204:207], v[94:97]
	v_mfma_f32_16x16x32_bf16 v[94:97], v[146:149], v[208:211], v[94:97]
	v_mfma_f32_16x16x32_bf16 v[90:93], v[138:141], v[208:211], v[90:93]
	v_mfma_f32_16x16x32_bf16 v[90:93], v[134:137], v[204:207], v[90:93]
	s_setprio 0
	s_setprio 1
	v_mfma_f32_16x16x32_bf16 v[98:101], v[150:153], v[180:183], v[98:101]
	v_mfma_f32_16x16x32_bf16 v[98:101], v[154:157], v[184:187], v[98:101]
	v_mfma_f32_16x16x32_bf16 v[102:105], v[172:175], v[184:187], v[102:105]
	v_mfma_f32_16x16x32_bf16 v[102:105], v[158:161], v[180:183], v[102:105]
	v_mfma_f32_16x16x32_bf16 v[110:113], v[158:161], v[188:191], v[110:113]
	v_mfma_f32_16x16x32_bf16 v[110:113], v[172:175], v[192:195], v[110:113]
	v_mfma_f32_16x16x32_bf16 v[106:109], v[154:157], v[192:195], v[106:109]
	v_mfma_f32_16x16x32_bf16 v[106:109], v[150:153], v[188:191], v[106:109]
	v_mfma_f32_16x16x32_bf16 v[114:117], v[150:153], v[196:199], v[114:117]
	v_mfma_f32_16x16x32_bf16 v[114:117], v[154:157], v[200:203], v[114:117]
	v_mfma_f32_16x16x32_bf16 v[118:121], v[172:175], v[200:203], v[118:121]
	v_mfma_f32_16x16x32_bf16 v[118:121], v[158:161], v[196:199], v[118:121]
	v_mfma_f32_16x16x32_bf16 v[126:129], v[158:161], v[204:207], v[126:129]
	v_mfma_f32_16x16x32_bf16 v[126:129], v[172:175], v[208:211], v[126:129]
	v_mfma_f32_16x16x32_bf16 v[122:125], v[154:157], v[208:211], v[122:125]
	v_mfma_f32_16x16x32_bf16 v[122:125], v[150:153], v[204:207], v[122:125]
	s_setprio 0
	s_barrier
	s_add_i32 s54, 0, 0x18000
	s_add_i32 s55, 0, 0x1c000
	v_add_u32_e32 v146, s54, v178
	v_add_u32_e32 v172, s55, v178
	ds_read_b128 v[134:137], v146
	ds_read_b128 v[138:141], v146 offset:1024
	ds_read_b128 v[142:145], v146 offset:2048
	ds_read_b128 v[146:149], v146 offset:3072
	ds_read_b128 v[150:153], v172
	ds_read_b128 v[154:157], v172 offset:1024
	ds_read_b128 v[158:161], v172 offset:2048
	ds_read_b128 v[172:175], v172 offset:3072
	s_add_u32 s40, s40, 0x80000
	s_addc_u32 s41, s41, 0
	s_mov_b32 m0, s33
	ds_read_b128 v[180:183], v179 offset:32768
	ds_read_b128 v[184:187], v179 offset:33792
	ds_read_b128 v[188:191], v179 offset:34816
	ds_read_b128 v[192:195], v179 offset:35840
	ds_read_b128 v[196:199], v179 offset:36864
	ds_read_b128 v[200:203], v179 offset:37888
	ds_read_b128 v[204:207], v179 offset:38912
	ds_read_b128 v[208:211], v179 offset:39936
	global_load_lds_dwordx4 v162, s[40:41]
	s_mov_b32 m0, s36
	s_nop 0
	global_load_lds_dwordx4 v164, s[40:41]
	s_waitcnt vmcnt(8)
	s_waitcnt lgkmcnt(0)
	s_barrier
	s_setprio 1
	s_waitcnt lgkmcnt(0)
	v_mfma_f32_16x16x32_bf16 v[82:85], v[134:137], v[180:183], v[82:85]
	v_mfma_f32_16x16x32_bf16 v[82:85], v[138:141], v[184:187], v[82:85]
	v_mfma_f32_16x16x32_bf16 v[78:81], v[146:149], v[184:187], v[78:81]
	v_mfma_f32_16x16x32_bf16 v[78:81], v[142:145], v[180:183], v[78:81]
	v_mfma_f32_16x16x32_bf16 v[70:73], v[142:145], v[188:191], v[70:73]
	v_mfma_f32_16x16x32_bf16 v[70:73], v[146:149], v[192:195], v[70:73]
	v_mfma_f32_16x16x32_bf16 v[74:77], v[138:141], v[192:195], v[74:77]
	v_mfma_f32_16x16x32_bf16 v[74:77], v[134:137], v[188:191], v[74:77]
	v_mfma_f32_16x16x32_bf16 v[66:69], v[134:137], v[196:199], v[66:69]
	v_mfma_f32_16x16x32_bf16 v[66:69], v[138:141], v[200:203], v[66:69]
	v_mfma_f32_16x16x32_bf16 v[62:65], v[146:149], v[200:203], v[62:65]
	v_mfma_f32_16x16x32_bf16 v[62:65], v[142:145], v[196:199], v[62:65]
	v_mfma_f32_16x16x32_bf16 v[54:57], v[142:145], v[204:207], v[54:57]
	v_mfma_f32_16x16x32_bf16 v[54:57], v[146:149], v[208:211], v[54:57]
	v_mfma_f32_16x16x32_bf16 v[58:61], v[138:141], v[208:211], v[58:61]
	v_mfma_f32_16x16x32_bf16 v[58:61], v[134:137], v[204:207], v[58:61]
	s_setprio 0
	s_setprio 1
	v_mfma_f32_16x16x32_bf16 v[50:53], v[150:153], v[180:183], v[50:53]
	v_mfma_f32_16x16x32_bf16 v[50:53], v[154:157], v[184:187], v[50:53]
	v_mfma_f32_16x16x32_bf16 v[46:49], v[172:175], v[184:187], v[46:49]
	v_mfma_f32_16x16x32_bf16 v[46:49], v[158:161], v[180:183], v[46:49]
	v_mfma_f32_16x16x32_bf16 v[38:41], v[158:161], v[188:191], v[38:41]
	v_mfma_f32_16x16x32_bf16 v[38:41], v[172:175], v[192:195], v[38:41]
	v_mfma_f32_16x16x32_bf16 v[42:45], v[154:157], v[192:195], v[42:45]
	v_mfma_f32_16x16x32_bf16 v[42:45], v[150:153], v[188:191], v[42:45]
	v_mfma_f32_16x16x32_bf16 v[34:37], v[150:153], v[196:199], v[34:37]
	v_mfma_f32_16x16x32_bf16 v[34:37], v[154:157], v[200:203], v[34:37]
	v_mfma_f32_16x16x32_bf16 v[28:31], v[172:175], v[200:203], v[28:31]
	v_mfma_f32_16x16x32_bf16 v[28:31], v[158:161], v[196:199], v[28:31]
	v_mfma_f32_16x16x32_bf16 v[20:23], v[158:161], v[204:207], v[20:23]
	v_mfma_f32_16x16x32_bf16 v[20:23], v[172:175], v[208:211], v[20:23]
	v_mfma_f32_16x16x32_bf16 v[24:27], v[154:157], v[208:211], v[24:27]
	v_mfma_f32_16x16x32_bf16 v[24:27], v[150:153], v[204:207], v[24:27]
	s_setprio 0
	s_barrier
	s_add_i32 s40, s54, s13
	v_lshl_add_u64 v[212:213], v[212:213], 0, s[34:35]
	s_mov_b32 m0, s40
	ds_read_b128 v[180:183], v179 offset:49152
	ds_read_b128 v[184:187], v179 offset:50176
	ds_read_b128 v[188:191], v179 offset:51200
	ds_read_b128 v[192:195], v179 offset:52224
	ds_read_b128 v[196:199], v179 offset:53248
	ds_read_b128 v[200:203], v179 offset:54272
	ds_read_b128 v[204:207], v179 offset:55296
	ds_read_b128 v[208:211], v179 offset:56320
	global_load_lds_dwordx4 v[212:213], off
	s_add_i32 m0, s40, 0x2000
	s_add_u32 s38, s38, 0x80080
	v_lshl_add_u64 v[212:213], v[214:215], 0, s[34:35]
	s_addc_u32 s39, s39, 0
	s_add_i32 s40, s55, s13
	global_load_lds_dwordx4 v[212:213], off
	s_mov_b32 m0, s40
	s_nop 0
	global_load_lds_dwordx4 v32, s[38:39]
	s_add_i32 m0, s40, 0x2000
	s_nop 0
	global_load_lds_dwordx4 v166, s[38:39]
	v_lshl_add_u64 v[212:213], v[216:217], 0, s[34:35]
	s_mov_b32 m0, s43
	s_nop 0
	global_load_lds_dwordx4 v[212:213], off
	v_lshl_add_u64 v[212:213], v[220:221], 0, s[34:35]
	s_mov_b32 m0, s44
	s_nop 0
	global_load_lds_dwordx4 v[212:213], off
	s_waitcnt vmcnt(8)
	s_waitcnt lgkmcnt(0)
	s_barrier
	s_setprio 1
	s_waitcnt lgkmcnt(0)
	v_mfma_f32_16x16x32_bf16 v[16:19], v[134:137], v[180:183], v[16:19]
	v_mfma_f32_16x16x32_bf16 v[16:19], v[138:141], v[184:187], v[16:19]
	v_mfma_f32_16x16x32_bf16 v[12:15], v[146:149], v[184:187], v[12:15]
	v_mfma_f32_16x16x32_bf16 v[12:15], v[142:145], v[180:183], v[12:15]
	v_mfma_f32_16x16x32_bf16 v[4:7], v[142:145], v[188:191], v[4:7]
	v_mfma_f32_16x16x32_bf16 v[4:7], v[146:149], v[192:195], v[4:7]
	v_mfma_f32_16x16x32_bf16 v[8:11], v[138:141], v[192:195], v[8:11]
	v_mfma_f32_16x16x32_bf16 v[8:11], v[134:137], v[188:191], v[8:11]
	v_mfma_f32_16x16x32_bf16 v[0:3], v[134:137], v[196:199], v[0:3]
	v_mfma_f32_16x16x32_bf16 v[0:3], v[138:141], v[200:203], v[0:3]
	v_mfma_f32_16x16x32_bf16 v[86:89], v[146:149], v[200:203], v[86:89]
	v_mfma_f32_16x16x32_bf16 v[86:89], v[142:145], v[196:199], v[86:89]
	v_mfma_f32_16x16x32_bf16 v[94:97], v[142:145], v[204:207], v[94:97]
	v_mfma_f32_16x16x32_bf16 v[94:97], v[146:149], v[208:211], v[94:97]
	v_mfma_f32_16x16x32_bf16 v[90:93], v[138:141], v[208:211], v[90:93]
	v_mfma_f32_16x16x32_bf16 v[90:93], v[134:137], v[204:207], v[90:93]
	s_setprio 0
	s_setprio 1
	v_mfma_f32_16x16x32_bf16 v[98:101], v[150:153], v[180:183], v[98:101]
	v_mfma_f32_16x16x32_bf16 v[98:101], v[154:157], v[184:187], v[98:101]
	v_mfma_f32_16x16x32_bf16 v[102:105], v[172:175], v[184:187], v[102:105]
	v_mfma_f32_16x16x32_bf16 v[102:105], v[158:161], v[180:183], v[102:105]
	v_mfma_f32_16x16x32_bf16 v[110:113], v[158:161], v[188:191], v[110:113]
	v_mfma_f32_16x16x32_bf16 v[110:113], v[172:175], v[192:195], v[110:113]
	v_mfma_f32_16x16x32_bf16 v[106:109], v[154:157], v[192:195], v[106:109]
	v_mfma_f32_16x16x32_bf16 v[106:109], v[150:153], v[188:191], v[106:109]
	v_mfma_f32_16x16x32_bf16 v[114:117], v[150:153], v[196:199], v[114:117]
	v_mfma_f32_16x16x32_bf16 v[114:117], v[154:157], v[200:203], v[114:117]
	v_mfma_f32_16x16x32_bf16 v[118:121], v[172:175], v[200:203], v[118:121]
	v_mfma_f32_16x16x32_bf16 v[118:121], v[158:161], v[196:199], v[118:121]
	v_mfma_f32_16x16x32_bf16 v[126:129], v[158:161], v[204:207], v[126:129]
	v_mfma_f32_16x16x32_bf16 v[126:129], v[172:175], v[208:211], v[126:129]
	v_mfma_f32_16x16x32_bf16 v[122:125], v[154:157], v[208:211], v[122:125]
	v_mfma_f32_16x16x32_bf16 v[122:125], v[150:153], v[204:207], v[122:125]
	s_setprio 0
	s_barrier
	s_add_i32 s53, s53, 2
	s_add_u32 s30, s30, 0x100
	s_addc_u32 s31, s31, 0
	s_cmp_gt_u32 s53, 29
	s_cbranch_scc0 .LBB0_888
	s_and_b64 vcc, exec, s[18:19]
	s_cbranch_vccz .LBB0_891
	s_barrier
